# FFN-up main K-loop: leading wave group waits for its tile loads after its MFMA block (two loop versions selected by wave half)
# baseline (speedup 1.0000x reference)
; #define PG8_STAGE(bufoff, gbase, voff) do { _Pragma("unroll") for (int _i = 0; _i < 2; ++_i) \
;         __builtin_amdgcn_global_load_lds((const unsigned*)((const char*)(gbase) + (voff)[_i]), (LAS unsigned*)(lds + (bufoff) + ldsw + _i * 8192), 16, 0, 0); } while (0)
; #define PG8_LDA(dst, b, h) do { _Pragma("unroll") for (int m = 0; m < 4; ++m) _Pragma("unroll") for (int k = 0; k < 2; ++k) dst[m][k] = *(const LAS bf16x8*)(lds + PG8_SA(b, h) + aoff + m * 2048 + k * 1024); } while (0)
; #define PG8_LDB(dst, b, h) do { _Pragma("unroll") for (int n = 0; n < 2; ++n) _Pragma("unroll") for (int k = 0; k < 2; ++k) dst[n][k] = *(const LAS bf16x8*)(lds + PG8_SB(b, h) + boff + n * 2048 + k * 1024); } while (0)
; #define PG8_WAIT_V(n) asm volatile("s_waitcnt vmcnt(" #n ")" ::: "memory")
; #define PG8_WAIT_L(n) asm volatile("s_waitcnt lgkmcnt(" #n ")" ::: "memory")
; template <class Epi, class Sched>
; __device__ __forceinline__ void gemm_phase(const int tid, LAS unsigned char* lds, const int lda, const int ldb, const int K, const Sched& S, const Epi& E) {
;     ...
;     for (;;) {
;         const bool has_next = S.next(ui + 1, nxt);
;         const char* nA = has_next ? nxt.a : cA; const char* nB = has_next ? nxt.b : cB;
;         for (int t = 0; t < nt; t += 2) {
;             const bool last = (t == nt - 2);
;             const char* a1 = cA + (size_t)(t + 1) * kstep;
;             const char* a2 = last ? nA : cA + (size_t)(t + 2) * kstep; const char* b2 = last ? nB : cB + (size_t)(t + 2) * kstep;
;             const char* a3 = a2 + kstep; const char* b3 = b2 + kstep;
;             PG8_LDB(B0, 0, 0); PG8_LDB(B1, 0, 1); PG8_SCHED; PG8_LDA(At, 0, 0); PG8_STAGE(PG8_SA(1, 1), a1 + hstepA, voffA);
;             PG8_WAIT_V(8); PG8_WAIT_L(0); PG8_BAR; PG8_MMA(0, 0, At, B0); PG8_MMA(0, 1, At, B1); PG8_BAR; PG8_SCHED;
;             PG8_LDA(At, 0, 1); PG8_STAGE(PG8_SB(0, 0), b2, voffB); PG8_STAGE(PG8_SB(0, 1), b2 + hstepB, voffB); PG8_STAGE(PG8_SA(0, 0), a2, voffA);
;             PG8_WAIT_V(8); PG8_WAIT_L(0); PG8_BAR; if (!cur.half) { PG8_MMA(1, 0, At, B0); PG8_MMA(1, 1, At, B1); } PG8_BAR; PG8_SCHED;
;             PG8_LDB(B0, 1, 0); PG8_LDB(B1, 1, 1); PG8_SCHED; PG8_LDA(At, 1, 0); PG8_STAGE(PG8_SA(0, 1), a2 + hstepA, voffA);
;             PG8_WAIT_V(8); PG8_WAIT_L(0); PG8_BAR; PG8_MMA(0, 0, At, B0); PG8_MMA(0, 1, At, B1); PG8_BAR; PG8_SCHED;
.LBB0_896:
	s_cmp_eq_u32 s42, 0
	s_cbranch_scc1 .Lw1_0_896
.Lw0_0_896:
	s_add_i32 s65, s52, 2
	s_add_u32 s24, s50, 0xfffc0080
	s_addc_u32 s53, s51, -1
	s_add_i32 s66, 0, 0x10000
	s_cmp_eq_u32 s61, s52
	s_cselect_b32 s55, s3, s53
	s_cselect_b32 s54, s2, s24
	v_add_u32_e32 v166, s66, v146
	s_cselect_b32 s53, s39, s64
	s_cselect_b32 s52, s38, s45
	s_add_i32 s24, 0, 0x14000
	ds_read_b128 v[154:157], v166
	ds_read_b128 v[158:161], v166 offset:1024
	ds_read_b128 v[162:165], v166 offset:2048
	ds_read_b128 v[180:183], v166 offset:3072
	v_add_u32_e32 v166, s24, v146
	ds_read_b128 v[184:187], v166
	ds_read_b128 v[190:193], v166 offset:1024
	ds_read_b128 v[194:197], v166 offset:2048
	ds_read_b128 v[204:207], v166 offset:3072
	v_lshl_add_u64 v[166:167], s[50:51], 0, v[136:137]
	s_add_i32 m0, s29, 0xc000
	ds_read_b128 v[208:211], v153
	ds_read_b128 v[212:215], v153 offset:1024
	ds_read_b128 v[216:219], v153 offset:2048
	ds_read_b128 v[220:223], v153 offset:3072
	ds_read_b128 v[224:227], v153 offset:4096
	ds_read_b128 v[228:231], v153 offset:5120
	ds_read_b128 v[232:235], v153 offset:6144
	ds_read_b128 v[236:239], v153 offset:7168
	global_load_lds_dwordx4 v[166:167], off
	v_lshl_add_u64 v[166:167], s[50:51], 0, v[138:139]
	s_add_i32 m0, s29, 0xe000
	s_nop 0
	global_load_lds_dwordx4 v[166:167], off
	s_waitcnt lgkmcnt(0)
	s_barrier
	s_setprio 1
	v_mfma_f32_16x16x32_bf16 v[124:127], v[154:157], v[208:211], v[124:127]
	v_mfma_f32_16x16x32_bf16 v[116:119], v[162:165], v[208:211], v[116:119]
	v_mfma_f32_16x16x32_bf16 v[108:111], v[154:157], v[216:219], v[108:111]
	v_mfma_f32_16x16x32_bf16 v[100:103], v[162:165], v[216:219], v[100:103]
	v_mfma_f32_16x16x32_bf16 v[92:95], v[154:157], v[224:227], v[92:95]
	v_mfma_f32_16x16x32_bf16 v[84:87], v[162:165], v[224:227], v[84:87]
	v_mfma_f32_16x16x32_bf16 v[76:79], v[154:157], v[232:235], v[76:79]
	v_mfma_f32_16x16x32_bf16 v[68:71], v[162:165], v[232:235], v[68:71]
	v_mfma_f32_16x16x32_bf16 v[124:127], v[158:161], v[212:215], v[124:127]
	v_mfma_f32_16x16x32_bf16 v[116:119], v[180:183], v[212:215], v[116:119]
	v_mfma_f32_16x16x32_bf16 v[108:111], v[158:161], v[220:223], v[108:111]
	v_mfma_f32_16x16x32_bf16 v[100:103], v[180:183], v[220:223], v[100:103]
	v_mfma_f32_16x16x32_bf16 v[92:95], v[158:161], v[228:231], v[92:95]
	v_mfma_f32_16x16x32_bf16 v[84:87], v[180:183], v[228:231], v[84:87]
	v_mfma_f32_16x16x32_bf16 v[76:79], v[158:161], v[236:239], v[76:79]
	v_mfma_f32_16x16x32_bf16 v[68:71], v[180:183], v[236:239], v[68:71]
	v_mfma_f32_16x16x32_bf16 v[120:123], v[184:187], v[208:211], v[120:123]
	v_mfma_f32_16x16x32_bf16 v[112:115], v[194:197], v[208:211], v[112:115]
	v_mfma_f32_16x16x32_bf16 v[104:107], v[184:187], v[216:219], v[104:107]
	v_mfma_f32_16x16x32_bf16 v[96:99], v[194:197], v[216:219], v[96:99]
	v_mfma_f32_16x16x32_bf16 v[88:91], v[184:187], v[224:227], v[88:91]
	v_mfma_f32_16x16x32_bf16 v[80:83], v[194:197], v[224:227], v[80:83]
	v_mfma_f32_16x16x32_bf16 v[72:75], v[184:187], v[232:235], v[72:75]
	v_mfma_f32_16x16x32_bf16 v[64:67], v[194:197], v[232:235], v[64:67]
	v_mfma_f32_16x16x32_bf16 v[120:123], v[190:193], v[212:215], v[120:123]
	v_mfma_f32_16x16x32_bf16 v[112:115], v[204:207], v[212:215], v[112:115]
	v_mfma_f32_16x16x32_bf16 v[104:107], v[190:193], v[220:223], v[104:107]
	v_mfma_f32_16x16x32_bf16 v[96:99], v[204:207], v[220:223], v[96:99]
	v_mfma_f32_16x16x32_bf16 v[88:91], v[190:193], v[228:231], v[88:91]
	v_mfma_f32_16x16x32_bf16 v[80:83], v[204:207], v[228:231], v[80:83]
	v_mfma_f32_16x16x32_bf16 v[72:75], v[190:193], v[236:239], v[72:75]
	v_mfma_f32_16x16x32_bf16 v[64:67], v[204:207], v[236:239], v[64:67]
	s_setprio 0
	s_waitcnt vmcnt(8)
	s_barrier
	s_add_i32 s66, s66, s20
	v_lshl_add_u64 v[166:167], s[52:53], 0, v[132:133]
	s_mov_b32 m0, s66
	ds_read_b128 v[208:211], v153 offset:16384
	ds_read_b128 v[212:215], v153 offset:17408
	ds_read_b128 v[216:219], v153 offset:18432
	ds_read_b128 v[220:223], v153 offset:19456
	ds_read_b128 v[224:227], v153 offset:20480
	ds_read_b128 v[228:231], v153 offset:21504
	ds_read_b128 v[232:235], v153 offset:22528
	ds_read_b128 v[236:239], v153 offset:23552
	global_load_lds_dwordx4 v[166:167], off
	s_add_i32 m0, s66, 0x2000
	s_add_u32 s66, s52, 0x40000
	v_lshl_add_u64 v[240:241], s[52:53], 0, v[128:129]
	s_addc_u32 s67, s53, 0
	s_add_i32 s24, s24, s20
	global_load_lds_dwordx4 v[240:241], off
	v_lshl_add_u64 v[242:243], s[66:67], 0, v[132:133]
	s_mov_b32 m0, s24
	v_lshl_add_u64 v[244:245], s[54:55], 0, v[130:131]
	global_load_lds_dwordx4 v[242:243], off
	v_lshl_add_u64 v[242:243], s[66:67], 0, v[128:129]
	s_add_i32 m0, s24, 0x2000
	s_nop 0
	global_load_lds_dwordx4 v[242:243], off
	v_lshl_add_u64 v[242:243], s[54:55], 0, v[134:135]
	s_waitcnt lgkmcnt(0)
	s_barrier
; #define PG8_STAGE(bufoff, gbase, voff) do { _Pragma("unroll") for (int _i = 0; _i < 2; ++_i) \
;         __builtin_amdgcn_global_load_lds((const unsigned*)((const char*)(gbase) + (voff)[_i]), (LAS unsigned*)(lds + (bufoff) + ldsw + _i * 8192), 16, 0, 0); } while (0)
; #define PG8_LDA(dst, b, h) do { _Pragma("unroll") for (int m = 0; m < 4; ++m) _Pragma("unroll") for (int k = 0; k < 2; ++k) dst[m][k] = *(const LAS bf16x8*)(lds + PG8_SA(b, h) + aoff + m * 2048 + k * 1024); } while (0)
; #define PG8_LDB(dst, b, h) do { _Pragma("unroll") for (int n = 0; n < 2; ++n) _Pragma("unroll") for (int k = 0; k < 2; ++k) dst[n][k] = *(const LAS bf16x8*)(lds + PG8_SB(b, h) + boff + n * 2048 + k * 1024); } while (0)
; #define PG8_MMA(ai, bj, At, Bt) do { __builtin_amdgcn_s_setprio(1); _Pragma("unroll") for (int m = 0; m < 4; ++m) _Pragma("unroll") for (int n = 0; n < 2; ++n) _Pragma("unroll") for (int k = 0; k < 2; ++k) \
;         acc[ai][bj][m][n] = __builtin_amdgcn_mfma_f32_16x16x32_bf16(Bt[n][k], At[m][k], acc[ai][bj][m][n], 0, 0, 0); __builtin_amdgcn_s_setprio(0); } while (0)
; #define PG8_WAIT_V(n) asm volatile("s_waitcnt vmcnt(" #n ")" ::: "memory")
; #define PG8_WAIT_L(n) asm volatile("s_waitcnt lgkmcnt(" #n ")" ::: "memory")
; #define PG8_BAR __builtin_amdgcn_s_barrier()
; #define PG8_SCHED __builtin_amdgcn_sched_barrier(0)
; template <class Epi, class Sched>
; __device__ __forceinline__ void gemm_phase(const int tid, LAS unsigned char* lds, const int lda, const int ldb, const int K, const Sched& S, const Epi& E) {
;     ...
;             PG8_WAIT_V(8); PG8_WAIT_L(0); PG8_BAR; if (!cur.half) { PG8_MMA(1, 0, At, B0); PG8_MMA(1, 1, At, B1); } PG8_BAR; PG8_SCHED;
;             PG8_LDB(B0, 1, 0); PG8_LDB(B1, 1, 1); PG8_SCHED; PG8_LDA(At, 1, 0); PG8_STAGE(PG8_SA(0, 1), a2 + hstepA, voffA);
;             PG8_WAIT_V(8); PG8_WAIT_L(0); PG8_BAR; PG8_MMA(0, 0, At, B0); PG8_MMA(0, 1, At, B1); PG8_BAR; PG8_SCHED;
	s_setprio 1
	v_mfma_f32_16x16x32_bf16 v[60:63], v[154:157], v[208:211], v[60:63]
	v_mfma_f32_16x16x32_bf16 v[52:55], v[162:165], v[208:211], v[52:55]
	v_mfma_f32_16x16x32_bf16 v[44:47], v[154:157], v[216:219], v[44:47]
	v_mfma_f32_16x16x32_bf16 v[36:39], v[162:165], v[216:219], v[36:39]
	v_mfma_f32_16x16x32_bf16 v[28:31], v[154:157], v[224:227], v[28:31]
	v_mfma_f32_16x16x32_bf16 v[20:23], v[162:165], v[224:227], v[20:23]
	v_mfma_f32_16x16x32_bf16 v[12:15], v[154:157], v[232:235], v[12:15]
	v_mfma_f32_16x16x32_bf16 v[4:7], v[162:165], v[232:235], v[4:7]
	v_mfma_f32_16x16x32_bf16 v[60:63], v[158:161], v[212:215], v[60:63]
	v_mfma_f32_16x16x32_bf16 v[52:55], v[180:183], v[212:215], v[52:55]
	v_mfma_f32_16x16x32_bf16 v[44:47], v[158:161], v[220:223], v[44:47]
	v_mfma_f32_16x16x32_bf16 v[36:39], v[180:183], v[220:223], v[36:39]
	v_mfma_f32_16x16x32_bf16 v[28:31], v[158:161], v[228:231], v[28:31]
	v_mfma_f32_16x16x32_bf16 v[20:23], v[180:183], v[228:231], v[20:23]
	v_mfma_f32_16x16x32_bf16 v[12:15], v[158:161], v[236:239], v[12:15]
	v_mfma_f32_16x16x32_bf16 v[4:7], v[180:183], v[236:239], v[4:7]
	v_mfma_f32_16x16x32_bf16 v[56:59], v[184:187], v[208:211], v[56:59]
	v_mfma_f32_16x16x32_bf16 v[48:51], v[194:197], v[208:211], v[48:51]
	v_mfma_f32_16x16x32_bf16 v[40:43], v[184:187], v[216:219], v[40:43]
	v_mfma_f32_16x16x32_bf16 v[32:35], v[194:197], v[216:219], v[32:35]
	v_mfma_f32_16x16x32_bf16 v[24:27], v[184:187], v[224:227], v[24:27]
	v_mfma_f32_16x16x32_bf16 v[16:19], v[194:197], v[224:227], v[16:19]
	v_mfma_f32_16x16x32_bf16 v[8:11], v[184:187], v[232:235], v[8:11]
	v_mfma_f32_16x16x32_bf16 v[0:3], v[194:197], v[232:235], v[0:3]
	v_mfma_f32_16x16x32_bf16 v[56:59], v[190:193], v[212:215], v[56:59]
	v_mfma_f32_16x16x32_bf16 v[48:51], v[204:207], v[212:215], v[48:51]
	v_mfma_f32_16x16x32_bf16 v[40:43], v[190:193], v[220:223], v[40:43]
	v_mfma_f32_16x16x32_bf16 v[32:35], v[204:207], v[220:223], v[32:35]
	v_mfma_f32_16x16x32_bf16 v[24:27], v[190:193], v[228:231], v[24:27]
	v_mfma_f32_16x16x32_bf16 v[16:19], v[204:207], v[228:231], v[16:19]
	v_mfma_f32_16x16x32_bf16 v[8:11], v[190:193], v[236:239], v[8:11]
	v_mfma_f32_16x16x32_bf16 v[0:3], v[204:207], v[236:239], v[0:3]
	s_setprio 0
	s_waitcnt vmcnt(6)
	s_barrier
	s_add_i32 s24, 0, 0x18000
	v_add_u32_e32 v176, s24, v146
	s_add_i32 s66, 0, 0x1c000
	ds_read_b128 v[154:157], v176
	ds_read_b128 v[158:161], v176 offset:1024
	ds_read_b128 v[162:165], v176 offset:2048
	ds_read_b128 v[180:183], v176 offset:3072
	v_add_u32_e32 v176, s66, v146
	ds_read_b128 v[184:187], v176
	ds_read_b128 v[190:193], v176 offset:1024
	ds_read_b128 v[194:197], v176 offset:2048
	ds_read_b128 v[204:207], v176 offset:3072
	s_mov_b32 m0, s29
	s_nop 0
	global_load_lds_dwordx4 v[242:243], off
	s_mov_b32 m0, s31
	s_nop 0
	global_load_lds_dwordx4 v[244:245], off
	s_add_u32 s54, s54, 0x40000
	s_addc_u32 s55, s55, 0
	s_mov_b32 m0, s56
	v_lshl_add_u64 v[246:247], s[54:55], 0, v[134:135]
	ds_read_b128 v[208:211], v153 offset:32768
	ds_read_b128 v[212:215], v153 offset:33792
	ds_read_b128 v[216:219], v153 offset:34816
	ds_read_b128 v[220:223], v153 offset:35840
	ds_read_b128 v[224:227], v153 offset:36864
	ds_read_b128 v[228:231], v153 offset:37888
	ds_read_b128 v[232:235], v153 offset:38912
	ds_read_b128 v[236:239], v153 offset:39936
	global_load_lds_dwordx4 v[246:247], off
	v_lshl_add_u64 v[246:247], s[54:55], 0, v[130:131]
	s_mov_b32 m0, s57
	s_nop 0
	global_load_lds_dwordx4 v[246:247], off
	s_waitcnt lgkmcnt(0)
	s_barrier
	s_setprio 1
	v_mfma_f32_16x16x32_bf16 v[124:127], v[154:157], v[208:211], v[124:127]
	v_mfma_f32_16x16x32_bf16 v[116:119], v[162:165], v[208:211], v[116:119]
	v_mfma_f32_16x16x32_bf16 v[108:111], v[154:157], v[216:219], v[108:111]
	v_mfma_f32_16x16x32_bf16 v[100:103], v[162:165], v[216:219], v[100:103]
	v_mfma_f32_16x16x32_bf16 v[92:95], v[154:157], v[224:227], v[92:95]
	v_mfma_f32_16x16x32_bf16 v[84:87], v[162:165], v[224:227], v[84:87]
	v_mfma_f32_16x16x32_bf16 v[76:79], v[154:157], v[232:235], v[76:79]
	v_mfma_f32_16x16x32_bf16 v[68:71], v[162:165], v[232:235], v[68:71]
	v_mfma_f32_16x16x32_bf16 v[124:127], v[158:161], v[212:215], v[124:127]
	v_mfma_f32_16x16x32_bf16 v[116:119], v[180:183], v[212:215], v[116:119]
	v_mfma_f32_16x16x32_bf16 v[108:111], v[158:161], v[220:223], v[108:111]
	v_mfma_f32_16x16x32_bf16 v[100:103], v[180:183], v[220:223], v[100:103]
	v_mfma_f32_16x16x32_bf16 v[92:95], v[158:161], v[228:231], v[92:95]
	v_mfma_f32_16x16x32_bf16 v[84:87], v[180:183], v[228:231], v[84:87]
	v_mfma_f32_16x16x32_bf16 v[76:79], v[158:161], v[236:239], v[76:79]
	v_mfma_f32_16x16x32_bf16 v[68:71], v[180:183], v[236:239], v[68:71]
	v_mfma_f32_16x16x32_bf16 v[120:123], v[184:187], v[208:211], v[120:123]
	v_mfma_f32_16x16x32_bf16 v[112:115], v[194:197], v[208:211], v[112:115]
	v_mfma_f32_16x16x32_bf16 v[104:107], v[184:187], v[216:219], v[104:107]
	v_mfma_f32_16x16x32_bf16 v[96:99], v[194:197], v[216:219], v[96:99]
	v_mfma_f32_16x16x32_bf16 v[88:91], v[184:187], v[224:227], v[88:91]
	v_mfma_f32_16x16x32_bf16 v[80:83], v[194:197], v[224:227], v[80:83]
	v_mfma_f32_16x16x32_bf16 v[72:75], v[184:187], v[232:235], v[72:75]
	v_mfma_f32_16x16x32_bf16 v[64:67], v[194:197], v[232:235], v[64:67]
	v_mfma_f32_16x16x32_bf16 v[120:123], v[190:193], v[212:215], v[120:123]
	v_mfma_f32_16x16x32_bf16 v[112:115], v[204:207], v[212:215], v[112:115]
	v_mfma_f32_16x16x32_bf16 v[104:107], v[190:193], v[220:223], v[104:107]
	v_mfma_f32_16x16x32_bf16 v[96:99], v[204:207], v[220:223], v[96:99]
	v_mfma_f32_16x16x32_bf16 v[88:91], v[190:193], v[228:231], v[88:91]
	v_mfma_f32_16x16x32_bf16 v[80:83], v[204:207], v[228:231], v[80:83]
	v_mfma_f32_16x16x32_bf16 v[72:75], v[190:193], v[236:239], v[72:75]
	v_mfma_f32_16x16x32_bf16 v[64:67], v[204:207], v[236:239], v[64:67]
	s_setprio 0
	s_waitcnt vmcnt(8)
	s_barrier
; #define PG8_STAGE(bufoff, gbase, voff) do { _Pragma("unroll") for (int _i = 0; _i < 2; ++_i) \
;         __builtin_amdgcn_global_load_lds((const unsigned*)((const char*)(gbase) + (voff)[_i]), (LAS unsigned*)(lds + (bufoff) + ldsw + _i * 8192), 16, 0, 0); } while (0)
; #define PG8_LDA(dst, b, h) do { _Pragma("unroll") for (int m = 0; m < 4; ++m) _Pragma("unroll") for (int k = 0; k < 2; ++k) dst[m][k] = *(const LAS bf16x8*)(lds + PG8_SA(b, h) + aoff + m * 2048 + k * 1024); } while (0)
; #define PG8_MMA(ai, bj, At, Bt) do { __builtin_amdgcn_s_setprio(1); _Pragma("unroll") for (int m = 0; m < 4; ++m) _Pragma("unroll") for (int n = 0; n < 2; ++n) _Pragma("unroll") for (int k = 0; k < 2; ++k) \
;         acc[ai][bj][m][n] = __builtin_amdgcn_mfma_f32_16x16x32_bf16(Bt[n][k], At[m][k], acc[ai][bj][m][n], 0, 0, 0); __builtin_amdgcn_s_setprio(0); } while (0)
; #define PG8_WAIT_V(n) asm volatile("s_waitcnt vmcnt(" #n ")" ::: "memory")
; #define PG8_WAIT_L(n) asm volatile("s_waitcnt lgkmcnt(" #n ")" ::: "memory")
; #define PG8_BAR __builtin_amdgcn_s_barrier()
; #define PG8_SCHED __builtin_amdgcn_sched_barrier(0)
; template <class Epi, class Sched>
; __device__ __forceinline__ void gemm_phase(const int tid, LAS unsigned char* lds, const int lda, const int ldb, const int K, const Sched& S, const Epi& E) {
;     ...
;             PG8_LDA(At, 1, 1); PG8_STAGE(PG8_SB(1, 0), b3, voffB); PG8_STAGE(PG8_SB(1, 1), b3 + hstepB, voffB); PG8_STAGE(PG8_SA(1, 0), a3, voffA);
;             PG8_WAIT_V(8); PG8_WAIT_L(0); PG8_BAR; if (!cur.half) { PG8_MMA(1, 0, At, B0); PG8_MMA(1, 1, At, B1); } PG8_BAR; PG8_SCHED;
;         }
	s_add_i32 s24, s24, s20
	v_lshl_add_u64 v[166:167], v[166:167], 0, s[6:7]
	s_mov_b32 m0, s24
	ds_read_b128 v[208:211], v153 offset:49152
	ds_read_b128 v[212:215], v153 offset:50176
	ds_read_b128 v[216:219], v153 offset:51200
	ds_read_b128 v[220:223], v153 offset:52224
	ds_read_b128 v[224:227], v153 offset:53248
	ds_read_b128 v[228:231], v153 offset:54272
	ds_read_b128 v[232:235], v153 offset:55296
	ds_read_b128 v[236:239], v153 offset:56320
	global_load_lds_dwordx4 v[166:167], off
	s_add_i32 m0, s24, 0x2000
	s_add_u32 s52, s52, 0x40080
	v_lshl_add_u64 v[166:167], v[240:241], 0, s[6:7]
	s_addc_u32 s53, s53, 0
	s_add_i32 s24, s66, s20
	global_load_lds_dwordx4 v[166:167], off
	v_lshl_add_u64 v[166:167], s[52:53], 0, v[132:133]
	s_mov_b32 m0, s24
	s_nop 0
	global_load_lds_dwordx4 v[166:167], off
	v_lshl_add_u64 v[166:167], s[52:53], 0, v[128:129]
	s_add_i32 m0, s24, 0x2000
	s_nop 0
	global_load_lds_dwordx4 v[166:167], off
	v_lshl_add_u64 v[166:167], v[242:243], 0, s[6:7]
	s_mov_b32 m0, s58
	s_nop 0
	global_load_lds_dwordx4 v[166:167], off
	v_lshl_add_u64 v[166:167], v[244:245], 0, s[6:7]
	s_mov_b32 m0, s59
	s_nop 0
	global_load_lds_dwordx4 v[166:167], off
	s_waitcnt lgkmcnt(0)
	s_barrier
	s_setprio 1
	v_mfma_f32_16x16x32_bf16 v[60:63], v[154:157], v[208:211], v[60:63]
	v_mfma_f32_16x16x32_bf16 v[52:55], v[162:165], v[208:211], v[52:55]
	v_mfma_f32_16x16x32_bf16 v[44:47], v[154:157], v[216:219], v[44:47]
	v_mfma_f32_16x16x32_bf16 v[36:39], v[162:165], v[216:219], v[36:39]
	v_mfma_f32_16x16x32_bf16 v[28:31], v[154:157], v[224:227], v[28:31]
	v_mfma_f32_16x16x32_bf16 v[20:23], v[162:165], v[224:227], v[20:23]
	v_mfma_f32_16x16x32_bf16 v[12:15], v[154:157], v[232:235], v[12:15]
	v_mfma_f32_16x16x32_bf16 v[4:7], v[162:165], v[232:235], v[4:7]
	v_mfma_f32_16x16x32_bf16 v[60:63], v[158:161], v[212:215], v[60:63]
	v_mfma_f32_16x16x32_bf16 v[52:55], v[180:183], v[212:215], v[52:55]
	v_mfma_f32_16x16x32_bf16 v[44:47], v[158:161], v[220:223], v[44:47]
	v_mfma_f32_16x16x32_bf16 v[36:39], v[180:183], v[220:223], v[36:39]
	v_mfma_f32_16x16x32_bf16 v[28:31], v[158:161], v[228:231], v[28:31]
	v_mfma_f32_16x16x32_bf16 v[20:23], v[180:183], v[228:231], v[20:23]
	v_mfma_f32_16x16x32_bf16 v[12:15], v[158:161], v[236:239], v[12:15]
	v_mfma_f32_16x16x32_bf16 v[4:7], v[180:183], v[236:239], v[4:7]
	v_mfma_f32_16x16x32_bf16 v[56:59], v[184:187], v[208:211], v[56:59]
	v_mfma_f32_16x16x32_bf16 v[48:51], v[194:197], v[208:211], v[48:51]
	v_mfma_f32_16x16x32_bf16 v[40:43], v[184:187], v[216:219], v[40:43]
	v_mfma_f32_16x16x32_bf16 v[32:35], v[194:197], v[216:219], v[32:35]
	v_mfma_f32_16x16x32_bf16 v[24:27], v[184:187], v[224:227], v[24:27]
	v_mfma_f32_16x16x32_bf16 v[16:19], v[194:197], v[224:227], v[16:19]
	v_mfma_f32_16x16x32_bf16 v[8:11], v[184:187], v[232:235], v[8:11]
	v_mfma_f32_16x16x32_bf16 v[0:3], v[194:197], v[232:235], v[0:3]
	v_mfma_f32_16x16x32_bf16 v[56:59], v[190:193], v[212:215], v[56:59]
	v_mfma_f32_16x16x32_bf16 v[48:51], v[204:207], v[212:215], v[48:51]
	v_mfma_f32_16x16x32_bf16 v[40:43], v[190:193], v[220:223], v[40:43]
	v_mfma_f32_16x16x32_bf16 v[32:35], v[204:207], v[220:223], v[32:35]
	v_mfma_f32_16x16x32_bf16 v[24:27], v[190:193], v[228:231], v[24:27]
	v_mfma_f32_16x16x32_bf16 v[16:19], v[204:207], v[228:231], v[16:19]
	v_mfma_f32_16x16x32_bf16 v[8:11], v[190:193], v[236:239], v[8:11]
	v_mfma_f32_16x16x32_bf16 v[0:3], v[204:207], v[236:239], v[0:3]
	s_setprio 0
	s_waitcnt vmcnt(8)
	s_barrier
	s_add_u32 s50, s50, 0x100
	s_addc_u32 s51, s51, 0
	s_add_u32 s45, s45, 0x100
	s_addc_u32 s64, s64, 0
	s_cmp_ge_i32 s65, s13
	s_mov_b32 s52, s65
	s_cbranch_scc0 .Lw0_0_896
	s_branch .Lwx_0_896

; #define PG8_BAR __builtin_amdgcn_s_barrier()
; template <class Epi, class Sched>
; __device__ __forceinline__ void gemm_phase(const int tid, LAS unsigned char* lds, const int lda, const int ldb, const int K, const Sched& S, const Epi& E) {
;     ...
;         if (wr == 0) PG8_BAR;
.Lwx_0_896:
.Lkexit_896:
	s_mov_b32 s65, 0x12000
	s_mov_b32 s64, 0x14000
	s_mov_b32 s66, 0x16000
	s_mov_b32 s67, 0x18000
	s_and_b64 vcc, exec, s[42:43]
	s_cbranch_vccz .LBB0_899
